# attention: xor-16/32 exchanges of q-norm, row max and row sum via v_permlane16/32_swap instead of ds_bpermute
# speedup vs baseline: 1.0028x; 1.0015x over previous
; #define LAS __attribute__((address_space(3)))
; __device__ __forceinline__ float bflo(unsigned u) { return __uint_as_float(u << 16); }
; __device__ __forceinline__ void attn_phase(LAS unsigned char* lds, const bf16* PROJ, const bf16* Ygate, bf16* OG0, bf16* OG1, bf16* OG2, float* LSE, const float* qnw, const float* knw, int bx, int G) {
;     ...
;         const int sub = t & 15, gi = (t >> 4) % 3, bh = t / 48, h = bh & 15, bl = bh >> 4;
;         const int sh = 2 * gi, d = 1 << sh, r = sub & (d - 1), n = sub >> sh;
;         const float ad = exp2f(-8.f * (float)(gi * 16 + h + 1) / 48.f) * (float)d;
;         bf16* OG = gi == 0 ? OG0 : (gi == 1 ? OG1 : OG2);
;         {
;             const f32x4 kw0 = *(const f32x4*)(knw + gi * 64 + 8 * oct), kw1 = *(const f32x4*)(knw + gi * 64 + 8 * oct + 4);
; #pragma unroll
;             for (int jj = 0; jj < 4; ++jj) {
;                 const int key = (tid >> 3) + 64 * jj; const v4u kq = kr[half][jj];
;                 float kf[8] = {bflo(kq.x), bfhi(kq.x), bflo(kq.y), bfhi(kq.y), bflo(kq.z), bfhi(kq.z), bflo(kq.w), bfhi(kq.w)};
;                 float ss = 0.f;
; #pragma unroll
;                 for (int e = 0; e < 8; ++e) ss += kf[e] * kf[e];
;                 ss += __shfl_xor(ss, 1); ss += __shfl_xor(ss, 2); ss += __shfl_xor(ss, 4);
;                 const float rs = rsqrtf(ss * (1.f / 64.f) + EPS);
;                 v4u ko; ko.x = pk2(kf[0] * rs * kw0[0], kf[1] * rs * kw0[1]); ko.y = pk2(kf[2] * rs * kw0[2], kf[3] * rs * kw0[3]);
;                 ko.z = pk2(kf[4] * rs * kw1[0], kf[5] * rs * kw1[1]); ko.w = pk2(kf[6] * rs * kw1[2], kf[7] * rs * kw1[3]);
;                 *(LAS v4u*)(Ks + key * 72 + 8 * oct) = ko;
;                 *(LAS v4u*)(Vs + key * 80 + 8 * oct) = vr[half][jj];
;             }
;         }
;         const int qi = 16 * w + l16;
;         const size_t qrow = (size_t)bl * SEQL + (size_t)(128 * n + qi) * d + r;
;         bf16x8 qreg[2];
;         {
;             float qf[2][8]; float ss = 0.f;
; #pragma unroll
;             for (int ks = 0; ks < 2; ++ks) {
;                 const v4u qq = qr[half][ks];
;                 qf[ks][0] = bflo(qq.x); qf[ks][1] = bfhi(qq.x); qf[ks][2] = bflo(qq.y); qf[ks][3] = bfhi(qq.y); qf[ks][4] = bflo(qq.z); qf[ks][5] = bfhi(qq.z); qf[ks][6] = bflo(qq.w); qf[ks][7] = bfhi(qq.w);
; #pragma unroll
;                 for (int e = 0; e < 8; ++e) ss += qf[ks][e] * qf[ks][e];
.LBB0_269:
	s_ashr_i32 s0, s51, 4
	s_mul_hi_i32 s1, s0, 0x55555556
	s_lshr_b32 s2, s1, 31
	s_add_i32 s1, s1, s2
	s_mul_i32 s1, s1, 3
	s_sub_i32 s2, s0, s1
	s_mul_hi_i32 s0, s51, 0x2aaaaaab
	s_lshl_b32 s3, s2, 1
	s_and_b32 s20, s51, 15
	s_lshr_b32 s1, s0, 31
	s_ashr_i32 s21, s0, 3
	s_bfm_b32 s0, s3, 0
	s_and_b32 s22, s0, s20
	s_lshl_b32 s0, s2, 6
	s_add_i32 s21, s21, s1
	s_ashr_i32 s1, s0, 31
	s_lshl_b64 s[24:25], s[0:1], 2
	v_lshl_add_u64 v[2:3], v[110:111], 0, s[24:25]
	global_load_dwordx4 v[84:87], v[2:3], off offset:16
	global_load_dwordx4 v[88:91], v[2:3], off
	s_waitcnt vmcnt(5)
	v_lshlrev_b32_e32 v102, 16, v8
	v_and_b32_e32 v103, 0xffff0000, v8
	v_lshlrev_b32_e32 v98, 16, v9
	v_and_b32_e32 v99, 0xffff0000, v9
	v_pk_mul_f32 v[104:105], v[102:103], v[102:103]
	v_pk_mul_f32 v[100:101], v[98:99], v[98:99]
	v_add_f32_e32 v1, v104, v105
	v_lshlrev_b32_e32 v94, 16, v10
	v_and_b32_e32 v95, 0xffff0000, v10
	v_add_f32_e32 v1, v100, v1
	v_pk_mul_f32 v[96:97], v[94:95], v[94:95]
	v_add_f32_e32 v1, v101, v1
	v_lshlrev_b32_e32 v2, 16, v11
	v_and_b32_e32 v3, 0xffff0000, v11
	v_add_f32_e32 v1, v96, v1
	v_pk_mul_f32 v[92:93], v[2:3], v[2:3]
	v_add_f32_e32 v1, v97, v1
	v_add_f32_e32 v1, v92, v1
	v_add_f32_e32 v1, v93, v1
	s_nop 1
	v_mov_b32_dpp v92, v1 quad_perm:[1,0,3,2] row_mask:0xf bank_mask:0xf
	v_lshlrev_b32_e32 v156, 16, v20
	v_and_b32_e32 v157, 0xffff0000, v20
	v_lshlrev_b32_e32 v152, 16, v21
	v_and_b32_e32 v153, 0xffff0000, v21
	s_waitcnt lgkmcnt(0)
	v_add_f32_e32 v1, v1, v92
	s_nop 1
	v_mov_b32_dpp v92, v1 quad_perm:[2,3,0,1] row_mask:0xf bank_mask:0xf
	v_pk_mul_f32 v[158:159], v[156:157], v[156:157]
	v_pk_mul_f32 v[154:155], v[152:153], v[152:153]
	v_mov_b32_e32 v162, v158
	v_lshlrev_b32_e32 v136, 16, v22
	s_waitcnt lgkmcnt(0)
	v_add_f32_e32 v1, v1, v92
	s_nop 1
	v_mov_b32_dpp v92, v1 row_half_mirror row_mask:0xf bank_mask:0xf
	v_and_b32_e32 v137, 0xffff0000, v22
	v_mov_b32_e32 v158, v154
	v_pk_mul_f32 v[150:151], v[136:137], v[136:137]
	v_lshlrev_b32_e32 v106, 16, v23
	s_waitcnt lgkmcnt(0)
	v_add_f32_e32 v1, v1, v92
	v_fmamk_f32 v1, v1, 0x3c800000, v139
	v_cmp_gt_f32_e32 vcc, s33, v1
	v_mul_f32_e32 v92, 0x4b800000, v1
	v_and_b32_e32 v107, 0xffff0000, v23
	v_cndmask_b32_e32 v1, v1, v92, vcc
	v_rsq_f32_e32 v1, v1
	v_pk_mul_f32 v[134:135], v[106:107], v[106:107]
	s_mov_b32 s0, 0x358637bd
	s_mov_b32 s26, 0x3c800000
	v_mul_f32_e32 v92, 0x45800000, v1
	v_cndmask_b32_e32 v96, v1, v92, vcc
	v_pk_mul_f32 v[92:93], v[96:97], v[102:103] op_sel_hi:[0,1]
	v_pk_mul_f32 v[98:99], v[96:97], v[98:99] op_sel_hi:[0,1]
	v_pk_mul_f32 v[94:95], v[96:97], v[94:95] op_sel_hi:[0,1]
	v_pk_mul_f32 v[2:3], v[96:97], v[2:3] op_sel_hi:[0,1]
	v_lshlrev_b32_e32 v102, 16, v4
	v_and_b32_e32 v103, 0xffff0000, v4
	v_pk_mul_f32 v[104:105], v[102:103], v[102:103]
	s_waitcnt vmcnt(3)
	v_and_b32_e32 v179, 0xffff0000, v48
	v_mov_b32_e32 v163, v104
	v_mov_b32_e32 v104, v159
	v_pk_add_f32 v[104:105], v[162:163], v[104:105]
	v_lshlrev_b32_e32 v178, 16, v48
	v_mul_f32_e32 v240, v179, v179
	v_lshlrev_b32_e32 v176, 16, v49
	v_and_b32_e32 v177, 0xffff0000, v49
	v_pk_fma_f32 v[240:241], v[178:179], v[178:179], v[240:241] op_sel_hi:[1,1,0]
	v_mul_f32_e32 v242, v177, v177
	v_pk_fma_f32 v[240:241], v[176:177], v[176:177], v[240:241]
	v_lshlrev_b32_e32 v174, 16, v50
	v_and_b32_e32 v175, 0xffff0000, v50
	v_pk_add_f32 v[240:241], v[242:243], v[240:241] op_sel_hi:[0,1]
	v_pk_fma_f32 v[240:241], v[174:175], v[174:175], v[240:241]
	v_mul_f32_e32 v242, v175, v175
	v_lshlrev_b32_e32 v172, 16, v51
	v_and_b32_e32 v173, 0xffff0000, v51
	v_pk_add_f32 v[240:241], v[242:243], v[240:241] op_sel_hi:[0,1]
	v_add_u32_e32 v231, v113, v188
	v_lshlrev_b32_e32 v162, 16, v40
	v_and_b32_e32 v163, 0xffff0000, v40
	s_waitcnt vmcnt(2)
	v_lshlrev_b32_e32 v170, 16, v52
	s_waitcnt vmcnt(1)
	v_pk_mul_f32 v[94:95], v[84:85], v[94:95]
	s_waitcnt vmcnt(0)
	v_pk_mul_f32 v[92:93], v[88:89], v[92:93]
	v_pk_mul_f32 v[98:99], v[90:91], v[98:99]
	v_cvt_pk_bf16_f32 v92, v92, v93
	v_cvt_pk_bf16_f32 v93, v98, v99
	v_pk_mul_f32 v[2:3], v[86:87], v[2:3]
	v_lshlrev_b32_e32 v98, 16, v5
	v_and_b32_e32 v99, 0xffff0000, v5
	v_cvt_pk_bf16_f32 v94, v94, v95
	v_cvt_pk_bf16_f32 v95, v2, v3
	v_pk_mul_f32 v[100:101], v[98:99], v[98:99]
	ds_write_b128 v229, v[92:95]
	v_lshlrev_b32_e32 v94, 16, v6
	v_and_b32_e32 v95, 0xffff0000, v6
	v_mov_b32_e32 v159, v100
	v_pk_mul_f32 v[96:97], v[94:95], v[94:95]
	v_pk_add_f32 v[104:105], v[158:159], v[104:105]
	v_mov_b32_e32 v100, v155
	v_lshlrev_b32_e32 v2, 16, v7
	v_and_b32_e32 v3, 0xffff0000, v7
	v_pk_add_f32 v[100:101], v[100:101], v[104:105]
	v_mov_b32_e32 v104, v150
	v_mov_b32_e32 v105, v96
	v_pk_mul_f32 v[92:93], v[2:3], v[2:3]
	v_pk_add_f32 v[100:101], v[104:105], v[100:101]
	v_mov_b32_e32 v96, v151
	v_pk_add_f32 v[96:97], v[96:97], v[100:101]
	v_mov_b32_e32 v100, v134
	v_mov_b32_e32 v101, v92
	v_pk_add_f32 v[96:97], v[100:101], v[96:97]
	v_mov_b32_e32 v92, v135
	v_pk_add_f32 v[92:93], v[92:93], v[96:97]
	s_nop 1
	v_mov_b32_dpp v97, v93 quad_perm:[1,0,3,2] row_mask:0xf bank_mask:0xf
	s_nop 1
	v_mov_b32_dpp v96, v92 quad_perm:[1,0,3,2] row_mask:0xf bank_mask:0xf
	v_mov_b64_e32 v[134:135], s[0:1]
	v_and_b32_e32 v171, 0xffff0000, v52
	v_pk_fma_f32 v[240:241], v[172:173], v[172:173], v[240:241]
	v_mul_f32_e32 v242, v173, v173
	s_waitcnt lgkmcnt(0)
	v_pk_add_f32 v[92:93], v[92:93], v[96:97]
	s_nop 1
	v_mov_b32_dpp v97, v93 quad_perm:[2,3,0,1] row_mask:0xf bank_mask:0xf
	s_nop 1
	v_mov_b32_dpp v96, v92 quad_perm:[2,3,0,1] row_mask:0xf bank_mask:0xf
	ds_write_b128 v231, v[12:15] offset:36864
	v_pk_mul_f32 v[180:181], v[162:163], v[162:163]
	v_pk_mul_f32 v[238:239], v[170:171], v[170:171]
	v_pk_add_f32 v[240:241], v[242:243], v[240:241] op_sel_hi:[0,1]
	s_waitcnt lgkmcnt(1)
; #define LAS __attribute__((address_space(3)))
; __device__ __forceinline__ void attn_phase(LAS unsigned char* lds, const bf16* PROJ, const bf16* Ygate, bf16* OG0, bf16* OG1, bf16* OG2, float* LSE, const float* qnw, const float* knw, int bx, int G) {
;     ...
;             for (int jj = 0; jj < 4; ++jj) {
;                 const int key = (tid >> 3) + 64 * jj; const v4u kq = kr[half][jj];
;                 float kf[8] = {bflo(kq.x), bfhi(kq.x), bflo(kq.y), bfhi(kq.y), bflo(kq.z), bfhi(kq.z), bflo(kq.w), bfhi(kq.w)};
;                 float ss = 0.f;
; #pragma unroll
;                 for (int e = 0; e < 8; ++e) ss += kf[e] * kf[e];
;                 ss += __shfl_xor(ss, 1); ss += __shfl_xor(ss, 2); ss += __shfl_xor(ss, 4);
;                 const float rs = rsqrtf(ss * (1.f / 64.f) + EPS);
;                 v4u ko; ko.x = pk2(kf[0] * rs * kw0[0], kf[1] * rs * kw0[1]); ko.y = pk2(kf[2] * rs * kw0[2], kf[3] * rs * kw0[3]);
;                 ko.z = pk2(kf[4] * rs * kw1[0], kf[5] * rs * kw1[1]); ko.w = pk2(kf[6] * rs * kw1[2], kf[7] * rs * kw1[3]);
;                 *(LAS v4u*)(Ks + key * 72 + 8 * oct) = ko;
;                 *(LAS v4u*)(Vs + key * 80 + 8 * oct) = vr[half][jj];
;             }
;         }
;         const int qi = 16 * w + l16;
;         const size_t qrow = (size_t)bl * SEQL + (size_t)(128 * n + qi) * d + r;
;         bf16x8 qreg[2];
;         {
;             float qf[2][8]; float ss = 0.f;
; #pragma unroll
;             for (int ks = 0; ks < 2; ++ks) {
;                 const v4u qq = qr[half][ks];
;                 qf[ks][0] = bflo(qq.x); qf[ks][1] = bfhi(qq.x); qf[ks][2] = bflo(qq.y); qf[ks][3] = bfhi(qq.y); qf[ks][4] = bflo(qq.z); qf[ks][5] = bfhi(qq.z); qf[ks][6] = bflo(qq.w); qf[ks][7] = bfhi(qq.w);
; #pragma unroll
;                 for (int e = 0; e < 8; ++e) ss += qf[ks][e] * qf[ks][e];
;             }
;             ss += __shfl_xor(ss, 16); ss += __shfl_xor(ss, 32);
;             const float rs = rsqrtf(ss * (1.f / 64.f) + EPS) * 0.125f;
; #pragma unroll
;             for (int ks = 0; ks < 2; ++ks) {
;                 const f32x4 w0 = *(const f32x4*)(qnw + gi * 64 + 32 * ks + 8 * g4), w1 = *(const f32x4*)(qnw + gi * 64 + 32 * ks + 8 * g4 + 4);
;                 v4u tq; tq.x = pk2(qf[ks][0] * rs * w0[0], qf[ks][1] * rs * w0[1]); tq.y = pk2(qf[ks][2] * rs * w0[2], qf[ks][3] * rs * w0[3]);
	v_pk_add_f32 v[92:93], v[92:93], v[96:97]
	s_nop 1
	v_mov_b32_dpp v97, v93 row_half_mirror row_mask:0xf bank_mask:0xf
	s_nop 1
	v_mov_b32_dpp v96, v92 row_half_mirror row_mask:0xf bank_mask:0xf
	v_lshlrev_b32_e32 v168, 16, v53
	v_and_b32_e32 v169, 0xffff0000, v53
	v_mov_b32_e32 v242, v238
	v_mov_b32_e32 v243, v180
	s_waitcnt lgkmcnt(0)
	v_pk_add_f32 v[92:93], v[92:93], v[96:97]
	v_mov_b32_e32 v241, v181
	v_pk_fma_f32 v[96:97], v[92:93], s[26:27], v[134:135] op_sel_hi:[1,0,0]
	v_pk_mul_f32 v[236:237], v[168:169], v[168:169]
	v_mul_f32_e32 v1, 0x4b800000, v97
	v_cmp_gt_f32_e64 s[0:1], s33, v97
	v_cmp_gt_f32_e32 vcc, s33, v96
	v_pk_add_f32 v[180:181], v[242:243], v[240:241]
	v_cndmask_b32_e64 v1, v97, v1, s[0:1]
	v_rsq_f32_e32 v1, v1
	v_lshlrev_b32_e32 v166, 16, v54
	v_and_b32_e32 v167, 0xffff0000, v54
	v_pk_mul_f32 v[234:235], v[166:167], v[166:167]
	v_mul_f32_e32 v92, 0x45800000, v1
	v_cndmask_b32_e64 v100, v1, v92, s[0:1]
	v_mul_f32_e32 v1, 0x4b800000, v96
	v_cndmask_b32_e32 v1, v96, v1, vcc
	v_rsq_f32_e32 v1, v1
	v_pk_mul_f32 v[94:95], v[100:101], v[94:95] op_sel_hi:[0,1]
	v_pk_mul_f32 v[2:3], v[100:101], v[2:3] op_sel_hi:[0,1]
	v_pk_mul_f32 v[92:93], v[100:101], v[102:103] op_sel_hi:[0,1]
	v_pk_mul_f32 v[98:99], v[100:101], v[98:99] op_sel_hi:[0,1]
	v_pk_mul_f32 v[94:95], v[84:85], v[94:95]
	v_pk_mul_f32 v[2:3], v[86:87], v[2:3]
	v_pk_mul_f32 v[92:93], v[88:89], v[92:93]
	v_pk_mul_f32 v[98:99], v[90:91], v[98:99]
	v_cvt_pk_bf16_f32 v94, v94, v95
	v_cvt_pk_bf16_f32 v95, v2, v3
	v_mul_f32_e32 v2, 0x45800000, v1
	v_cvt_pk_bf16_f32 v92, v92, v93
	v_cvt_pk_bf16_f32 v93, v98, v99
	v_cndmask_b32_e32 v2, v1, v2, vcc
	ds_write_b128 v229, v[92:95] offset:9216
	ds_write_b128 v231, v[16:19] offset:47104
	v_pk_mul_f32 v[92:93], v[2:3], v[156:157] op_sel_hi:[0,1]
	v_lshlrev_b32_e32 v156, 16, v41
	v_and_b32_e32 v157, 0xffff0000, v41
	v_pk_mul_f32 v[158:159], v[156:157], v[156:157]
	v_pk_mul_f32 v[94:95], v[2:3], v[152:153] op_sel_hi:[0,1]
	v_lshlrev_b32_e32 v152, 16, v42
	v_and_b32_e32 v153, 0xffff0000, v42
	v_pk_mov_b32 v[238:239], v[238:239], v[158:159] op_sel:[1,0]
	v_pk_mul_f32 v[92:93], v[88:89], v[92:93]
	v_pk_mul_f32 v[94:95], v[90:91], v[94:95]
	v_pk_mul_f32 v[154:155], v[152:153], v[152:153]
	v_pk_add_f32 v[180:181], v[238:239], v[180:181]
	v_mov_b32_e32 v158, v236
	v_cvt_pk_bf16_f32 v92, v92, v93
	v_cvt_pk_bf16_f32 v93, v94, v95
	v_pk_mul_f32 v[94:95], v[2:3], v[136:137] op_sel_hi:[0,1]
	v_lshlrev_b32_e32 v136, 16, v43
	v_and_b32_e32 v137, 0xffff0000, v43
	v_pk_add_f32 v[158:159], v[158:159], v[180:181]
	v_pk_mov_b32 v[180:181], v[236:237], v[154:155] op_sel:[1,0]
	v_pk_mul_f32 v[150:151], v[136:137], v[136:137]
	v_lshlrev_b32_e32 v164, 16, v55
	v_and_b32_e32 v165, 0xffff0000, v55
	v_pk_add_f32 v[158:159], v[180:181], v[158:159]
	v_mov_b32_e32 v154, v234
	v_pk_mul_f32 v[232:233], v[164:165], v[164:165]
	v_pk_add_f32 v[154:155], v[154:155], v[158:159]
	v_pk_mov_b32 v[158:159], v[234:235], v[150:151] op_sel:[1,0]
	v_mov_b32_e32 v150, v232
	v_pk_add_f32 v[154:155], v[158:159], v[154:155]
	v_pk_mul_f32 v[2:3], v[2:3], v[106:107] op_sel_hi:[0,1]
	v_pk_add_f32 v[150:151], v[150:151], v[154:155]
	s_nop 1
	v_mov_b32_dpp v155, v151 quad_perm:[1,0,3,2] row_mask:0xf bank_mask:0xf
	v_mov_b32_e32 v154, v233
	v_pk_mul_f32 v[94:95], v[84:85], v[94:95]
	v_pk_mul_f32 v[2:3], v[86:87], v[2:3]
	s_ashr_i32 s0, s21, 4
	s_waitcnt lgkmcnt(0)
	v_pk_add_f32 v[150:151], v[154:155], v[150:151]
	s_nop 1
	v_mov_b32_dpp v155, v151 quad_perm:[2,3,0,1] row_mask:0xf bank_mask:0xf
	v_mov_b32_e32 v154, v150
	s_nop 1
	v_permlane16_swap_b32_e32 v154, v150
	s_lshr_b32 s54, s20, s3
	v_cvt_pk_bf16_f32 v94, v94, v95
	v_cvt_pk_bf16_f32 v95, v2, v3
	s_ashr_i32 s1, s0, 31
	s_waitcnt lgkmcnt(0)
	v_pk_add_f32 v[150:151], v[150:151], v[154:155]
	s_nop 1
	v_mov_b32_dpp v155, v151 row_half_mirror row_mask:0xf bank_mask:0xf
	v_mov_b32_e32 v154, v150
	s_nop 1
	v_permlane32_swap_b32_e32 v154, v150
	v_lshl_add_u32 v2, s54, 7, v147
	s_and_b32 s53, s21, 15
	s_lshl_b64 s[20:21], s[0:1], 11
	v_ashrrev_i32_e32 v3, 31, v2
	s_waitcnt lgkmcnt(0)
	v_pk_add_f32 v[150:151], v[150:151], v[154:155]
	s_or_b32 s20, s20, s22
	v_pk_fma_f32 v[180:181], v[150:151], s[26:27], v[134:135] op_sel_hi:[1,0,0]
	v_lshlrev_b64 v[2:3], s3, v[2:3]
	v_mul_f32_e32 v1, 0x4b800000, v181
	v_cmp_gt_f32_e32 vcc, s33, v181
	ds_write_b128 v229, v[92:95] offset:18432
	ds_write_b128 v231, v[24:27] offset:57344
	v_cndmask_b32_e32 v1, v181, v1, vcc
	v_rsq_f32_e32 v1, v1
	v_lshl_add_u64 v[96:97], v[114:115], 0, s[24:25]
	s_lshl_b32 s26, s53, 7
	global_load_dwordx4 v[100:103], v[96:97], off offset:16
	global_load_dwordx4 v[104:107], v[96:97], off
	global_load_dwordx4 v[92:95], v[96:97], off offset:144
	s_nop 0
	global_load_dwordx4 v[96:99], v[96:97], off offset:128
	v_mul_f32_e32 v134, 0x45800000, v1
	v_cndmask_b32_e32 v134, v1, v134, vcc
	v_pk_mul_f32 v[150:151], v[134:135], v[162:163] op_sel_hi:[0,1]
	v_pk_mul_f32 v[88:89], v[88:89], v[150:151]
	v_pk_mul_f32 v[150:151], v[134:135], v[156:157] op_sel_hi:[0,1]
	v_pk_mul_f32 v[90:91], v[90:91], v[150:151]
	v_cvt_pk_bf16_f32 v88, v88, v89
	v_cvt_pk_bf16_f32 v89, v90, v91
	v_pk_mul_f32 v[90:91], v[134:135], v[152:153] op_sel_hi:[0,1]
	v_pk_mul_f32 v[84:85], v[84:85], v[90:91]
	v_cmp_gt_f32_e64 s[0:1], s33, v180
	v_cvt_pk_bf16_f32 v90, v84, v85
	v_pk_mul_f32 v[84:85], v[134:135], v[136:137] op_sel_hi:[0,1]
	v_lshl_add_u64 v[136:137], s[20:21], 0, v[2:3]
	v_lshlrev_b64 v[162:163], 11, v[136:137]
	v_pk_mul_f32 v[84:85], v[86:87], v[84:85]
	v_lshl_add_u64 v[2:3], s[28:29], 0, v[162:163]
	v_cvt_pk_bf16_f32 v91, v84, v85
	v_lshl_add_u64 v[2:3], v[2:3], 0, s[26:27]
	v_lshlrev_b32_e32 v134, 1, v112
	v_mov_b32_e32 v135, v0
	ds_write_b128 v229, v[88:91] offset:27648
	ds_write_b128 v230, v[44:47] offset:57344
	v_lshl_add_u64 v[2:3], v[2:3], 0, v[134:135]
	global_load_dwordx4 v[88:91], v[2:3], off
	global_load_dwordx4 v[84:87], v[2:3], off offset:64
	v_readlane_b32 s20, v252, 59
	s_add_i32 s52, s51, s20
	s_waitcnt lgkmcnt(0)
	s_barrier
; __device__ __forceinline__ void attn_phase(LAS unsigned char* lds, const bf16* PROJ, const bf16* Ygate, bf16* OG0, bf16* OG1, bf16* OG2, float* LSE, const float* qnw, const float* knw, int bx, int G) {
;     ...
;         if (t + 2 * G < 3072) AT_LOAD(t + 2 * G, half);
	s_cmpk_gt_i32 s52, 0xbff
	s_cselect_b64 s[24:25], -1, 0
	s_and_b64 vcc, exec, s[24:25]
	s_cbranch_vccnz .LBB0_279
	s_ashr_i32 s21, s52, 4
	s_mul_hi_i32 s22, s21, 0x55555556
	s_lshr_b32 s23, s22, 31
	s_add_i32 s22, s22, s23
	s_mul_i32 s22, s22, 3
	s_sub_i32 s21, s21, s22
	s_mul_hi_i32 s22, s52, 0x2aaaaaab
	s_lshr_b32 s23, s22, 31
	s_ashr_i32 s22, s22, 3
	s_lshl_b32 s26, s21, 1
	s_and_b32 s20, s52, 15
	s_add_i32 s23, s22, s23
	s_lshl_b32 s30, -1, s26
	s_andn2_b32 s30, s20, s30
	s_lshr_b32 s31, s20, s26
	s_lshl_b32 s20, s23, 6
	s_ashr_i32 s22, s23, 4
	s_mulk_i32 s21, 0xc00
	s_and_b32 s20, s20, 0x3c0
	s_or_b32 s20, s21, s20
	s_ashr_i32 s23, s22, 31
	s_lshl_b64 s[22:23], s[22:23], 11
	s_ashr_i32 s21, s20, 31
	s_lshl_b32 s55, s31, 7
	s_or_b32 s22, s22, s30
	s_lshl_b64 s[30:31], s[20:21], 1
	v_mov_b32_e32 v6, v0
	v_mov_b32_e32 v7, v0
	v_add_u32_e32 v48, s55, v182
	s_add_u32 s38, s34, s30
	v_mov_b32_e32 v4, v0
	v_mov_b32_e32 v5, v0
	v_mov_b64_e32 v[10:11], v[6:7]
	v_mov_b64_e32 v[14:15], v[6:7]
	s_addc_u32 s39, s35, s31
	v_cmp_lt_i32_e32 vcc, -1, v48
	v_mov_b64_e32 v[8:9], v[4:5]
	v_mov_b64_e32 v[12:13], v[4:5]
	s_and_saveexec_b64 s[30:31], vcc
	s_cbranch_execz .LBB0_272
	v_mov_b32_e32 v49, v0
	v_lshlrev_b64 v[2:3], s26, v[48:49]
	v_lshl_add_u64 v[2:3], v[2:3], 0, s[22:23]
	v_mov_b64_e32 v[8:9], s[38:39]
	s_movk_i32 s80, 0x4800
	v_mad_u64_u32 v[8:9], vcc, v2, s80, v[8:9]
	v_mov_b32_e32 v2, v9
	v_mad_u64_u32 v[2:3], vcc, v3, s80, v[2:3]
	v_mov_b32_e32 v9, v2
	v_lshlrev_b32_e32 v2, 1, v108
	v_mov_b32_e32 v3, v0
	v_lshl_add_u64 v[2:3], v[8:9], 0, v[2:3]
	v_add_co_u32_e32 v12, vcc, 0x1000, v2
	s_nop 1
	v_addc_co_u32_e32 v13, vcc, 0, v3, vcc
	global_load_dwordx4 v[8:11], v[2:3], off offset:2048
	s_nop 0
	global_load_dwordx4 v[12:15], v[12:13], off

; #define LAS __attribute__((address_space(3)))
; __device__ __forceinline__ unsigned pk2(float lo, float hi) { f32x2_t v = {lo, hi}; bf16x2_t b = __builtin_convertvector(v, bf16x2_t); return __builtin_bit_cast(unsigned, b); }
; __device__ __forceinline__ f32x4 mfma16(bf16x8 a, bf16x8 b, f32x4 c) { return __builtin_amdgcn_mfma_f32_16x16x32_bf16(a, b, c, 0, 0, 0); }
; __device__ __forceinline__ void attn_phase(LAS unsigned char* lds, const bf16* PROJ, const bf16* Ygate, bf16* OG0, bf16* OG1, bf16* OG2, float* LSE, const float* qnw, const float* knw, int bx, int G) {
;     ...
;         mx = fmaxf(mx, __shfl_xor(mx, 16)); mx = fmaxf(mx, __shfl_xor(mx, 32));
;         float sum = 0.f;
; #pragma unroll
;         for (int t9 = 0; t9 < 9; ++t9)
; #pragma unroll
;             for (int rr = 0; rr < 4; ++rr) { const float p = __expf(sc[t9][rr] - mx); sc[t9][rr] = p; sum += p; }
;         sum += __shfl_xor(sum, 16); sum += __shfl_xor(sum, 32);
;         const float lse = mx + __logf(sum), inv = 1.f / sum;
;         f32x4 oacc[4];
; #pragma unroll
;         for (int dt = 0; dt < 4; ++dt) oacc[dt] = (f32x4){0.f, 0.f, 0.f, 0.f};
; #pragma unroll
;         for (int k2 = 0; k2 < 5; ++k2) {
;             const int T0 = w + 2 * k2;
;             if (T0 + 1 >= tlo) {
;                 v4u bpu; bpu.x = pk2(sc[2 * k2][0], sc[2 * k2][1]); bpu.y = pk2(sc[2 * k2][2], sc[2 * k2][3]);
;                 if (k2 < 4) { bpu.z = pk2(sc[(2 * k2 + 1) % 9][0], sc[(2 * k2 + 1) % 9][1]); bpu.w = pk2(sc[(2 * k2 + 1) % 9][2], sc[(2 * k2 + 1) % 9][3]); } else { bpu.z = 0u; bpu.w = 0u; }
;                 const bf16x8 bp = __builtin_bit_cast(bf16x8, bpu);
;                 const LAS bf16* vb = Vs + (16 * T0 + 4 * g4 + (l16 >> 2)) * 80 + 8 * (l16 & 3);
; #pragma unroll
;                 for (int dt = 0; dt < 4; ++dt) {
;                     const int co = 32 * (dt >> 1) + 4 * (dt & 1);
;                     const v4i16_t lo = __builtin_amdgcn_ds_read_tr16_b64_v4i16((LAS v4i16_t*)(vb + co));
;                     v4i16_t hi = (v4i16_t){0, 0, 0, 0};
;                     if (k2 < 4) hi = __builtin_amdgcn_ds_read_tr16_b64_v4i16((LAS v4i16_t*)(vb + 16 * 80 + co));
;                     oacc[dt] = mfma16((bf16x8){lo[0], lo[1], lo[2], lo[3], hi[0], hi[1], hi[2], hi[3]}, bp, oacc[dt]);
.LBB0_298:
	v_mov_b32_e32 v98, v135
	s_nop 1
	v_permlane16_swap_b32_e32 v98, v135
	v_max_f32_e32 v99, v135, v135
	s_add_i32 s0, s0, -1
	s_cmp_lt_i32 s50, s0
	s_waitcnt lgkmcnt(0)
	v_max_f32_e32 v98, v98, v98
	v_max_f32_e32 v98, v99, v98
	v_mov_b32_e32 v99, v98
	s_nop 1
	v_permlane32_swap_b32_e32 v99, v98
	s_waitcnt lgkmcnt(0)
	v_max_f32_e32 v99, v99, v99
	v_max_f32_e32 v164, v98, v99
	v_sub_f32_e32 v98, v101, v164
	v_sub_f32_e32 v101, v165, v164
	v_mul_f32_e32 v101, 0x3fb8aa3b, v101
	v_exp_f32_e32 v245, v101
	v_sub_f32_e32 v101, v166, v164
	v_mul_f32_e32 v101, 0x3fb8aa3b, v101
	v_exp_f32_e32 v246, v101
	v_sub_f32_e32 v101, v167, v164
	v_mul_f32_e32 v101, 0x3fb8aa3b, v101
	v_exp_f32_e32 v247, v101
	v_sub_f32_e32 v101, v103, v164
	v_mul_f32_e32 v101, 0x3fb8aa3b, v101
	v_exp_f32_e32 v248, v101
	v_sub_f32_e32 v101, v102, v164
	v_mul_f32_e32 v101, 0x3fb8aa3b, v101
	v_exp_f32_e32 v249, v101
	v_sub_f32_e32 v101, v169, v164
	v_mul_f32_e32 v101, 0x3fb8aa3b, v101
	v_sub_f32_e32 v92, v92, v164
	v_exp_f32_e32 v250, v101
	v_sub_f32_e32 v101, v170, v164
	v_sub_f32_e32 v93, v93, v164
	v_mul_f32_e32 v92, 0x3fb8aa3b, v92
	v_mul_f32_e32 v101, 0x3fb8aa3b, v101
	v_sub_f32_e32 v94, v94, v164
	v_mul_f32_e32 v93, 0x3fb8aa3b, v93
	v_exp_f32_e32 v92, v92
	v_exp_f32_e32 v154, v101
	v_sub_f32_e32 v101, v168, v164
	v_sub_f32_e32 v3, v3, v164
	v_mul_f32_e32 v94, 0x3fb8aa3b, v94
	v_exp_f32_e32 v93, v93
	v_mul_f32_e32 v101, 0x3fb8aa3b, v101
	v_mul_f32_e32 v3, 0x3fb8aa3b, v3
	v_exp_f32_e32 v94, v94
	v_exp_f32_e32 v155, v101
	v_sub_f32_e32 v101, v175, v164
	v_exp_f32_e32 v99, v3
	v_mul_f32_e32 v101, 0x3fb8aa3b, v101
	v_add_f32_e32 v3, 0, v92
	v_exp_f32_e32 v180, v101
	v_sub_f32_e32 v101, v173, v164
	v_add_f32_e32 v3, v93, v3
	v_mul_f32_e32 v101, 0x3fb8aa3b, v101
	v_sub_f32_e32 v1, v1, v164
	v_add_f32_e32 v3, v94, v3
	v_exp_f32_e32 v181, v101
	v_sub_f32_e32 v101, v174, v164
	v_add_f32_e32 v104, v99, v3
	v_mul_f32_e32 v1, 0x3fb8aa3b, v1
	v_sub_f32_e32 v3, v100, v164
	v_mul_f32_e32 v101, 0x3fb8aa3b, v101
	v_exp_f32_e32 v1, v1
	v_mul_f32_e32 v3, 0x3fb8aa3b, v3
	v_exp_f32_e32 v232, v101
	v_sub_f32_e32 v101, v172, v164
	v_exp_f32_e32 v3, v3
	v_mul_f32_e32 v98, 0x3fb8aa3b, v98
	v_sub_f32_e32 v95, v95, v164
	v_mul_f32_e32 v101, 0x3fb8aa3b, v101
	v_exp_f32_e32 v98, v98
	v_mul_f32_e32 v95, 0x3fb8aa3b, v95
	v_exp_f32_e32 v233, v101
	v_sub_f32_e32 v101, v171, v164
	v_exp_f32_e32 v95, v95
	v_mul_f32_e32 v101, 0x3fb8aa3b, v101
	v_add_f32_e32 v100, v1, v104
	v_exp_f32_e32 v235, v101
	v_sub_f32_e32 v101, v177, v164
	v_add_f32_e32 v100, v3, v100
	v_mul_f32_e32 v101, 0x3fb8aa3b, v101
	v_add_f32_e32 v100, v98, v100
	v_exp_f32_e32 v239, v101
	v_sub_f32_e32 v101, v178, v164
	v_add_f32_e32 v100, v95, v100
	v_mul_f32_e32 v101, 0x3fb8aa3b, v101
	v_add_f32_e32 v100, v245, v100
	v_exp_f32_e32 v178, v101
	v_sub_f32_e32 v101, v176, v164
	v_add_f32_e32 v100, v246, v100
	v_mul_f32_e32 v101, 0x3fb8aa3b, v101
	v_add_f32_e32 v100, v247, v100
	v_exp_f32_e32 v240, v101
	v_sub_f32_e32 v101, v238, v164
	v_add_f32_e32 v100, v248, v100
	v_mul_f32_e32 v101, 0x3fb8aa3b, v101
	v_add_f32_e32 v100, v249, v100
	v_exp_f32_e32 v170, v101
	v_sub_f32_e32 v101, v236, v164
	v_add_f32_e32 v100, v250, v100
	v_mul_f32_e32 v101, 0x3fb8aa3b, v101
	v_add_f32_e32 v100, v154, v100
	v_exp_f32_e32 v171, v101
	v_sub_f32_e32 v101, v237, v164
	v_add_f32_e32 v100, v155, v100
	v_mul_f32_e32 v101, 0x3fb8aa3b, v101
	v_add_f32_e32 v100, v180, v100
	v_exp_f32_e32 v172, v101
	v_sub_f32_e32 v101, v234, v164
	v_add_f32_e32 v100, v181, v100
	v_mul_f32_e32 v101, 0x3fb8aa3b, v101
	v_add_f32_e32 v100, v232, v100
	v_exp_f32_e32 v173, v101
	v_sub_f32_e32 v101, v179, v164
	v_add_f32_e32 v100, v233, v100
	v_mul_f32_e32 v101, 0x3fb8aa3b, v101
	v_add_f32_e32 v100, v235, v100
	v_exp_f32_e32 v174, v101
	v_sub_f32_e32 v101, v242, v164
	v_add_f32_e32 v100, v239, v100
	v_mul_f32_e32 v101, 0x3fb8aa3b, v101
	v_add_f32_e32 v100, v178, v100
	v_exp_f32_e32 v175, v101
	v_sub_f32_e32 v101, v243, v164
	v_add_f32_e32 v100, v240, v100
	v_mul_f32_e32 v101, 0x3fb8aa3b, v101
	v_add_f32_e32 v100, v170, v100
	v_exp_f32_e32 v176, v101
	v_sub_f32_e32 v101, v241, v164
	v_add_f32_e32 v100, v171, v100
	v_mul_f32_e32 v101, 0x3fb8aa3b, v101
	v_add_f32_e32 v100, v172, v100
	v_exp_f32_e32 v177, v101
	v_sub_f32_e32 v101, v244, v164
	v_sub_f32_e32 v96, v96, v164
	v_add_f32_e32 v100, v173, v100
	v_mul_f32_e32 v101, 0x3fb8aa3b, v101
	v_mul_f32_e32 v96, 0x3fb8aa3b, v96
	v_add_f32_e32 v100, v174, v100
	v_exp_f32_e32 v166, v101
	v_exp_f32_e32 v167, v96
	v_sub_f32_e32 v96, v97, v164
	v_add_f32_e32 v100, v175, v100
	v_mul_f32_e32 v96, 0x3fb8aa3b, v96
	v_sub_f32_e32 v2, v2, v164
	v_add_f32_e32 v100, v176, v100
	v_exp_f32_e32 v168, v96
	v_mul_f32_e32 v2, 0x3fb8aa3b, v2
	v_add_f32_e32 v100, v177, v100
	v_exp_f32_e32 v169, v2
	v_add_f32_e32 v2, v166, v100
	v_add_f32_e32 v2, v167, v2
	v_add_f32_e32 v2, v168, v2
	v_add_f32_e32 v2, v169, v2
	v_mov_b32_e32 v96, v2
	s_nop 1
	v_permlane16_swap_b32_e32 v96, v2
	s_waitcnt lgkmcnt(0)
	v_add_f32_e32 v135, v2, v96
	v_mov_b32_e32 v165, v135
	s_nop 1
	v_permlane32_swap_b32_e32 v165, v135
	s_cbranch_scc1 .LBB0_300
	v_add_u32_e32 v2, v184, v224
	v_cvt_pk_bf16_f32 v92, v92, v93
	v_cvt_pk_bf16_f32 v93, v94, v99
	ds_read_b64_tr_b16 v[102:103], v2 offset:39424
	ds_read_b64_tr_b16 v[100:101], v2 offset:36864
	v_cvt_pk_bf16_f32 v95, v98, v95
	ds_read_b64_tr_b16 v[98:99], v2 offset:39432
	ds_read_b64_tr_b16 v[96:97], v2 offset:36872
	ds_read_b64_tr_b16 v[156:157], v2 offset:36928
	ds_read_b64_tr_b16 v[150:151], v2 offset:36936
	ds_read_b64_tr_b16 v[158:159], v2 offset:39488
	ds_read_b64_tr_b16 v[152:153], v2 offset:39496
	v_cvt_pk_bf16_f32 v94, v1, v3
	s_waitcnt lgkmcnt(6)
	s_nop 0
	v_mfma_f32_16x16x32_bf16 v[104:107], v[100:103], v[92:95], 0
	s_waitcnt lgkmcnt(4)
	v_mfma_f32_16x16x32_bf16 v[100:103], v[96:99], v[92:95], 0
	s_waitcnt lgkmcnt(1)
	v_mfma_f32_16x16x32_bf16 v[96:99], v[156:159], v[92:95], 0
	s_waitcnt lgkmcnt(0)
	v_mfma_f32_16x16x32_bf16 v[92:95], v[150:153], v[92:95], 0
	s_cmp_lt_i32 s44, s0
	s_cbranch_scc0 .LBB0_301
	s_branch .LBB0_302

; #define LAS __attribute__((address_space(3)))
; __device__ __forceinline__ float bflo(unsigned u) { return __uint_as_float(u << 16); }
; __device__ __forceinline__ void attn_phase(LAS unsigned char* lds, const bf16* PROJ, const bf16* Ygate, bf16* OG0, bf16* OG1, bf16* OG2, float* LSE, const float* qnw, const float* knw, int bx, int G) {
;     ...
;         const int sub = t & 15, gi = (t >> 4) % 3, bh = t / 48, h = bh & 15, bl = bh >> 4;
;         const int sh = 2 * gi, d = 1 << sh, r = sub & (d - 1), n = sub >> sh;
;         const float ad = exp2f(-8.f * (float)(gi * 16 + h + 1) / 48.f) * (float)d;
;         bf16* OG = gi == 0 ? OG0 : (gi == 1 ? OG1 : OG2);
;         {
;             const f32x4 kw0 = *(const f32x4*)(knw + gi * 64 + 8 * oct), kw1 = *(const f32x4*)(knw + gi * 64 + 8 * oct + 4);
; #pragma unroll
;             for (int jj = 0; jj < 4; ++jj) {
;                 const int key = (tid >> 3) + 64 * jj; const v4u kq = kr[half][jj];
;                 float kf[8] = {bflo(kq.x), bfhi(kq.x), bflo(kq.y), bfhi(kq.y), bflo(kq.z), bfhi(kq.z), bflo(kq.w), bfhi(kq.w)};
;                 float ss = 0.f;
; #pragma unroll
;                 for (int e = 0; e < 8; ++e) ss += kf[e] * kf[e];
;                 ss += __shfl_xor(ss, 1); ss += __shfl_xor(ss, 2); ss += __shfl_xor(ss, 4);
;                 const float rs = rsqrtf(ss * (1.f / 64.f) + EPS);
;                 v4u ko; ko.x = pk2(kf[0] * rs * kw0[0], kf[1] * rs * kw0[1]); ko.y = pk2(kf[2] * rs * kw0[2], kf[3] * rs * kw0[3]);
;                 ko.z = pk2(kf[4] * rs * kw1[0], kf[5] * rs * kw1[1]); ko.w = pk2(kf[6] * rs * kw1[2], kf[7] * rs * kw1[3]);
;                 *(LAS v4u*)(Ks + key * 72 + 8 * oct) = ko;
;                 *(LAS v4u*)(Vs + key * 80 + 8 * oct) = vr[half][jj];
;             }
;         }
;         const int qi = 16 * w + l16;
;         const size_t qrow = (size_t)bl * SEQL + (size_t)(128 * n + qi) * d + r;
;         bf16x8 qreg[2];
;         {
;             float qf[2][8]; float ss = 0.f;
; #pragma unroll
;             for (int ks = 0; ks < 2; ++ks) {
;                 const v4u qq = qr[half][ks];
;                 qf[ks][0] = bflo(qq.x); qf[ks][1] = bfhi(qq.x); qf[ks][2] = bflo(qq.y); qf[ks][3] = bfhi(qq.y); qf[ks][4] = bflo(qq.z); qf[ks][5] = bfhi(qq.z); qf[ks][6] = bflo(qq.w); qf[ks][7] = bfhi(qq.w);
; #pragma unroll
;                 for (int e = 0; e < 8; ++e) ss += qf[ks][e] * qf[ks][e];
.LBB0_308:
	s_or_b64 exec, exec, s[0:1]
	s_waitcnt lgkmcnt(0)
	s_barrier
	s_add_i32 s0, s84, s51
	s_cmpk_gt_i32 s0, 0xbff
	s_cbranch_scc1 .LBB0_268
	s_ashr_i32 s1, s0, 4
	s_mul_hi_i32 s2, s1, 0x55555556
	s_lshr_b32 s3, s2, 31
	s_add_i32 s2, s2, s3
	s_mul_i32 s2, s2, 3
	s_sub_i32 s2, s1, s2
	s_and_b32 s22, s0, 15
	s_mul_hi_i32 s0, s0, 0x2aaaaaab
	s_lshl_b32 s3, s2, 1
	s_lshr_b32 s1, s0, 31
	s_ashr_i32 s23, s0, 3
	s_bfm_b32 s0, s3, 0
	s_and_b32 s26, s0, s22
	s_lshl_b32 s0, s2, 6
	s_add_i32 s23, s23, s1
	s_ashr_i32 s1, s0, 31
	s_lshl_b64 s[20:21], s[0:1], 2
	v_lshl_add_u64 v[2:3], v[110:111], 0, s[20:21]
	global_load_dwordx4 v[84:87], v[2:3], off offset:16
	global_load_dwordx4 v[88:91], v[2:3], off
	v_lshlrev_b32_e32 v102, 16, v32
	v_and_b32_e32 v103, 0xffff0000, v32
	v_lshlrev_b32_e32 v98, 16, v33
	v_and_b32_e32 v99, 0xffff0000, v33
	v_pk_mul_f32 v[104:105], v[102:103], v[102:103]
	v_pk_mul_f32 v[100:101], v[98:99], v[98:99]
	v_add_f32_e32 v1, v104, v105
	v_lshlrev_b32_e32 v94, 16, v34
	v_and_b32_e32 v95, 0xffff0000, v34
	v_add_f32_e32 v1, v100, v1
	v_pk_mul_f32 v[96:97], v[94:95], v[94:95]
	v_add_f32_e32 v1, v101, v1
	v_lshlrev_b32_e32 v2, 16, v35
	v_and_b32_e32 v3, 0xffff0000, v35
	v_add_f32_e32 v1, v96, v1
	v_pk_mul_f32 v[92:93], v[2:3], v[2:3]
	v_add_f32_e32 v1, v97, v1
	v_add_f32_e32 v1, v92, v1
	v_add_f32_e32 v1, v93, v1
	s_nop 1
	v_mov_b32_dpp v92, v1 quad_perm:[1,0,3,2] row_mask:0xf bank_mask:0xf
	v_lshlrev_b32_e32 v158, 16, v60
	v_and_b32_e32 v159, 0xffff0000, v60
	v_lshlrev_b32_e32 v154, 16, v61
	v_and_b32_e32 v155, 0xffff0000, v61
	s_waitcnt lgkmcnt(0)
	v_add_f32_e32 v1, v1, v92
	s_nop 1
	v_mov_b32_dpp v92, v1 quad_perm:[2,3,0,1] row_mask:0xf bank_mask:0xf
	v_pk_mul_f32 v[162:163], v[158:159], v[158:159]
	v_pk_mul_f32 v[156:157], v[154:155], v[154:155]
	v_mov_b32_e32 v164, v162
	v_lshlrev_b32_e32 v150, 16, v62
	s_waitcnt lgkmcnt(0)
	v_add_f32_e32 v1, v1, v92
	s_nop 1
	v_mov_b32_dpp v92, v1 row_half_mirror row_mask:0xf bank_mask:0xf
	v_and_b32_e32 v151, 0xffff0000, v62
	v_mov_b32_e32 v162, v156
	v_pk_mul_f32 v[152:153], v[150:151], v[150:151]
	v_lshlrev_b32_e32 v106, 16, v63
	s_waitcnt lgkmcnt(0)
	v_add_f32_e32 v1, v1, v92
	v_fmamk_f32 v1, v1, 0x3c800000, v139
	v_cmp_gt_f32_e32 vcc, s33, v1
	v_mul_f32_e32 v92, 0x4b800000, v1
	v_and_b32_e32 v107, 0xffff0000, v63
	v_cndmask_b32_e32 v1, v1, v92, vcc
	v_rsq_f32_e32 v1, v1
	v_pk_mul_f32 v[136:137], v[106:107], v[106:107]
	s_mov_b32 s0, 0x358637bd
	s_mov_b32 s38, 0x3c800000
	v_mul_f32_e32 v92, 0x45800000, v1
	v_cndmask_b32_e32 v96, v1, v92, vcc
	v_pk_mul_f32 v[92:93], v[96:97], v[102:103] op_sel_hi:[0,1]
	v_pk_mul_f32 v[98:99], v[96:97], v[98:99] op_sel_hi:[0,1]
	v_pk_mul_f32 v[94:95], v[96:97], v[94:95] op_sel_hi:[0,1]
	v_pk_mul_f32 v[2:3], v[96:97], v[2:3] op_sel_hi:[0,1]
	v_lshlrev_b32_e32 v102, 16, v28
	v_and_b32_e32 v103, 0xffff0000, v28
	v_pk_mul_f32 v[104:105], v[102:103], v[102:103]
	v_and_b32_e32 v179, 0xffff0000, v76
	v_mov_b32_e32 v165, v104
	v_mov_b32_e32 v104, v163
	v_pk_add_f32 v[104:105], v[164:165], v[104:105]
	v_lshlrev_b32_e32 v178, 16, v76
	v_mul_f32_e32 v242, v179, v179
	v_lshlrev_b32_e32 v176, 16, v77
	v_and_b32_e32 v177, 0xffff0000, v77
	v_pk_fma_f32 v[242:243], v[178:179], v[178:179], v[242:243] op_sel_hi:[1,1,0]
	v_mul_f32_e32 v244, v177, v177
	v_pk_fma_f32 v[242:243], v[176:177], v[176:177], v[242:243]
	v_lshlrev_b32_e32 v174, 16, v78
	v_and_b32_e32 v175, 0xffff0000, v78
	v_pk_add_f32 v[242:243], v[244:245], v[242:243] op_sel_hi:[0,1]
	v_pk_fma_f32 v[242:243], v[174:175], v[174:175], v[242:243]
	v_mul_f32_e32 v244, v175, v175
	v_lshlrev_b32_e32 v172, 16, v79
	v_and_b32_e32 v173, 0xffff0000, v79
	v_pk_add_f32 v[242:243], v[244:245], v[242:243] op_sel_hi:[0,1]
	v_lshlrev_b32_e32 v232, 16, v68
	v_and_b32_e32 v233, 0xffff0000, v68
	v_lshlrev_b32_e32 v170, 16, v80
	v_and_b32_e32 v171, 0xffff0000, v80
	s_waitcnt vmcnt(1)
	v_pk_mul_f32 v[94:95], v[84:85], v[94:95]
	s_waitcnt vmcnt(0)
	v_pk_mul_f32 v[92:93], v[88:89], v[92:93]
	v_pk_mul_f32 v[98:99], v[90:91], v[98:99]
	v_cvt_pk_bf16_f32 v92, v92, v93
	v_cvt_pk_bf16_f32 v93, v98, v99
	v_pk_mul_f32 v[2:3], v[86:87], v[2:3]
	v_lshlrev_b32_e32 v98, 16, v29
	v_and_b32_e32 v99, 0xffff0000, v29
	v_cvt_pk_bf16_f32 v94, v94, v95
	v_cvt_pk_bf16_f32 v95, v2, v3
	v_pk_mul_f32 v[100:101], v[98:99], v[98:99]
	ds_write_b128 v229, v[92:95]
	ds_write_b128 v231, v[36:39] offset:36864
	v_lshlrev_b32_e32 v94, 16, v30
	v_and_b32_e32 v95, 0xffff0000, v30
	v_mov_b32_e32 v163, v100
	v_pk_mul_f32 v[96:97], v[94:95], v[94:95]
	v_pk_add_f32 v[104:105], v[162:163], v[104:105]
	v_mov_b32_e32 v100, v157
	v_lshlrev_b32_e32 v2, 16, v31
	v_and_b32_e32 v3, 0xffff0000, v31
	v_pk_add_f32 v[100:101], v[100:101], v[104:105]
	v_mov_b32_e32 v104, v152
	v_mov_b32_e32 v105, v96
	v_pk_mul_f32 v[92:93], v[2:3], v[2:3]
	v_pk_add_f32 v[100:101], v[104:105], v[100:101]
	v_mov_b32_e32 v96, v153
	v_pk_add_f32 v[96:97], v[96:97], v[100:101]
	v_mov_b32_e32 v100, v136
	v_mov_b32_e32 v101, v92
	v_pk_add_f32 v[96:97], v[100:101], v[96:97]
	v_mov_b32_e32 v92, v137
	v_pk_add_f32 v[92:93], v[92:93], v[96:97]
	s_nop 1
	v_mov_b32_dpp v97, v93 quad_perm:[1,0,3,2] row_mask:0xf bank_mask:0xf
	s_nop 1
	v_mov_b32_dpp v96, v92 quad_perm:[1,0,3,2] row_mask:0xf bank_mask:0xf
	v_mov_b64_e32 v[136:137], s[0:1]
	v_pk_fma_f32 v[242:243], v[172:173], v[172:173], v[242:243]
	v_mul_f32_e32 v244, v173, v173
	v_pk_mul_f32 v[180:181], v[232:233], v[232:233]
	s_waitcnt lgkmcnt(0)
	v_pk_add_f32 v[92:93], v[92:93], v[96:97]
	s_nop 1
	v_mov_b32_dpp v97, v93 quad_perm:[2,3,0,1] row_mask:0xf bank_mask:0xf
	s_nop 1
	v_mov_b32_dpp v96, v92 quad_perm:[2,3,0,1] row_mask:0xf bank_mask:0xf
	v_pk_mul_f32 v[240:241], v[170:171], v[170:171]
	v_pk_add_f32 v[242:243], v[244:245], v[242:243] op_sel_hi:[0,1]
	v_lshlrev_b32_e32 v168, 16, v81
	v_and_b32_e32 v169, 0xffff0000, v81
	s_waitcnt lgkmcnt(0)
; #define LAS __attribute__((address_space(3)))
; __device__ __forceinline__ void attn_phase(LAS unsigned char* lds, const bf16* PROJ, const bf16* Ygate, bf16* OG0, bf16* OG1, bf16* OG2, float* LSE, const float* qnw, const float* knw, int bx, int G) {
;     ...
;             for (int jj = 0; jj < 4; ++jj) {
;                 const int key = (tid >> 3) + 64 * jj; const v4u kq = kr[half][jj];
;                 float kf[8] = {bflo(kq.x), bfhi(kq.x), bflo(kq.y), bfhi(kq.y), bflo(kq.z), bfhi(kq.z), bflo(kq.w), bfhi(kq.w)};
;                 float ss = 0.f;
; #pragma unroll
;                 for (int e = 0; e < 8; ++e) ss += kf[e] * kf[e];
;                 ss += __shfl_xor(ss, 1); ss += __shfl_xor(ss, 2); ss += __shfl_xor(ss, 4);
;                 const float rs = rsqrtf(ss * (1.f / 64.f) + EPS);
;                 v4u ko; ko.x = pk2(kf[0] * rs * kw0[0], kf[1] * rs * kw0[1]); ko.y = pk2(kf[2] * rs * kw0[2], kf[3] * rs * kw0[3]);
;                 ko.z = pk2(kf[4] * rs * kw1[0], kf[5] * rs * kw1[1]); ko.w = pk2(kf[6] * rs * kw1[2], kf[7] * rs * kw1[3]);
;                 *(LAS v4u*)(Ks + key * 72 + 8 * oct) = ko;
;                 *(LAS v4u*)(Vs + key * 80 + 8 * oct) = vr[half][jj];
;             }
;         }
;         const int qi = 16 * w + l16;
;         const size_t qrow = (size_t)bl * SEQL + (size_t)(128 * n + qi) * d + r;
;         bf16x8 qreg[2];
;         {
;             float qf[2][8]; float ss = 0.f;
; #pragma unroll
;             for (int ks = 0; ks < 2; ++ks) {
;                 const v4u qq = qr[half][ks];
;                 qf[ks][0] = bflo(qq.x); qf[ks][1] = bfhi(qq.x); qf[ks][2] = bflo(qq.y); qf[ks][3] = bfhi(qq.y); qf[ks][4] = bflo(qq.z); qf[ks][5] = bfhi(qq.z); qf[ks][6] = bflo(qq.w); qf[ks][7] = bfhi(qq.w);
; #pragma unroll
;                 for (int e = 0; e < 8; ++e) ss += qf[ks][e] * qf[ks][e];
;             }
;             ss += __shfl_xor(ss, 16); ss += __shfl_xor(ss, 32);
;             const float rs = rsqrtf(ss * (1.f / 64.f) + EPS) * 0.125f;
; #pragma unroll
;             for (int ks = 0; ks < 2; ++ks) {
;                 const f32x4 w0 = *(const f32x4*)(qnw + gi * 64 + 32 * ks + 8 * g4), w1 = *(const f32x4*)(qnw + gi * 64 + 32 * ks + 8 * g4 + 4);
;                 v4u tq; tq.x = pk2(qf[ks][0] * rs * w0[0], qf[ks][1] * rs * w0[1]); tq.y = pk2(qf[ks][2] * rs * w0[2], qf[ks][3] * rs * w0[3]);
	v_pk_add_f32 v[92:93], v[92:93], v[96:97]
	s_nop 1
	v_mov_b32_dpp v97, v93 row_half_mirror row_mask:0xf bank_mask:0xf
	s_nop 1
	v_mov_b32_dpp v96, v92 row_half_mirror row_mask:0xf bank_mask:0xf
	v_mov_b32_e32 v244, v240
	v_mov_b32_e32 v245, v180
	v_mov_b32_e32 v243, v181
	v_pk_mul_f32 v[238:239], v[168:169], v[168:169]
	s_waitcnt lgkmcnt(0)
	v_pk_add_f32 v[92:93], v[92:93], v[96:97]
	v_pk_add_f32 v[180:181], v[244:245], v[242:243]
	v_pk_fma_f32 v[96:97], v[92:93], s[38:39], v[136:137] op_sel_hi:[1,0,0]
	v_lshlrev_b32_e32 v166, 16, v82
	v_mul_f32_e32 v1, 0x4b800000, v97
	v_cmp_gt_f32_e64 s[0:1], s33, v97
	v_cmp_gt_f32_e32 vcc, s33, v96
	v_and_b32_e32 v167, 0xffff0000, v82
	v_cndmask_b32_e64 v1, v97, v1, s[0:1]
	v_rsq_f32_e32 v1, v1
	v_pk_mul_f32 v[236:237], v[166:167], v[166:167]
	v_lshlrev_b32_e32 v164, 16, v83
	v_and_b32_e32 v165, 0xffff0000, v83
	v_mul_f32_e32 v92, 0x45800000, v1
	v_cndmask_b32_e64 v100, v1, v92, s[0:1]
	v_mul_f32_e32 v1, 0x4b800000, v96
	v_cndmask_b32_e32 v1, v96, v1, vcc
	v_rsq_f32_e32 v1, v1
	v_pk_mul_f32 v[94:95], v[100:101], v[94:95] op_sel_hi:[0,1]
	v_pk_mul_f32 v[2:3], v[100:101], v[2:3] op_sel_hi:[0,1]
	v_pk_mul_f32 v[92:93], v[100:101], v[102:103] op_sel_hi:[0,1]
	v_pk_mul_f32 v[98:99], v[100:101], v[98:99] op_sel_hi:[0,1]
	v_pk_mul_f32 v[94:95], v[84:85], v[94:95]
	v_pk_mul_f32 v[2:3], v[86:87], v[2:3]
	v_pk_mul_f32 v[92:93], v[88:89], v[92:93]
	v_pk_mul_f32 v[98:99], v[90:91], v[98:99]
	v_cvt_pk_bf16_f32 v94, v94, v95
	v_cvt_pk_bf16_f32 v95, v2, v3
	v_mul_f32_e32 v2, 0x45800000, v1
	v_cvt_pk_bf16_f32 v92, v92, v93
	v_cvt_pk_bf16_f32 v93, v98, v99
	v_cndmask_b32_e32 v2, v1, v2, vcc
	ds_write_b128 v229, v[92:95] offset:9216
	ds_write_b128 v231, v[56:59] offset:47104
	v_pk_mul_f32 v[92:93], v[2:3], v[158:159] op_sel_hi:[0,1]
	v_lshlrev_b32_e32 v158, 16, v69
	v_and_b32_e32 v159, 0xffff0000, v69
	v_pk_mul_f32 v[162:163], v[158:159], v[158:159]
	v_pk_mul_f32 v[94:95], v[2:3], v[154:155] op_sel_hi:[0,1]
	v_lshlrev_b32_e32 v154, 16, v70
	v_and_b32_e32 v155, 0xffff0000, v70
	v_pk_mov_b32 v[240:241], v[240:241], v[162:163] op_sel:[1,0]
	v_pk_mul_f32 v[92:93], v[88:89], v[92:93]
	v_pk_mul_f32 v[94:95], v[90:91], v[94:95]
	v_pk_mul_f32 v[156:157], v[154:155], v[154:155]
	v_pk_add_f32 v[180:181], v[240:241], v[180:181]
	v_mov_b32_e32 v162, v238
	v_cvt_pk_bf16_f32 v92, v92, v93
	v_cvt_pk_bf16_f32 v93, v94, v95
	v_pk_mul_f32 v[94:95], v[2:3], v[150:151] op_sel_hi:[0,1]
	v_lshlrev_b32_e32 v150, 16, v71
	v_and_b32_e32 v151, 0xffff0000, v71
	v_pk_add_f32 v[162:163], v[162:163], v[180:181]
	v_pk_mov_b32 v[180:181], v[238:239], v[156:157] op_sel:[1,0]
	v_pk_mul_f32 v[152:153], v[150:151], v[150:151]
	v_pk_add_f32 v[162:163], v[180:181], v[162:163]
	v_mov_b32_e32 v156, v236
	v_pk_mul_f32 v[234:235], v[164:165], v[164:165]
	v_pk_add_f32 v[156:157], v[156:157], v[162:163]
	v_pk_mov_b32 v[162:163], v[236:237], v[152:153] op_sel:[1,0]
	v_mov_b32_e32 v152, v234
	v_pk_add_f32 v[156:157], v[162:163], v[156:157]
	v_pk_mul_f32 v[2:3], v[2:3], v[106:107] op_sel_hi:[0,1]
	v_pk_add_f32 v[152:153], v[152:153], v[156:157]
	s_nop 1
	v_mov_b32_dpp v157, v153 quad_perm:[1,0,3,2] row_mask:0xf bank_mask:0xf
	v_mov_b32_e32 v156, v235
	v_pk_mul_f32 v[94:95], v[84:85], v[94:95]
	v_pk_mul_f32 v[2:3], v[86:87], v[2:3]
	s_ashr_i32 s0, s23, 4
	s_waitcnt lgkmcnt(0)
	v_pk_add_f32 v[152:153], v[156:157], v[152:153]
	s_nop 1
	v_mov_b32_dpp v157, v153 quad_perm:[2,3,0,1] row_mask:0xf bank_mask:0xf
	v_mov_b32_e32 v156, v152
	s_nop 1
	v_permlane16_swap_b32_e32 v156, v152
	s_lshr_b32 s54, s22, s3
	v_cvt_pk_bf16_f32 v94, v94, v95
	v_cvt_pk_bf16_f32 v95, v2, v3
	s_ashr_i32 s1, s0, 31
	s_waitcnt lgkmcnt(0)
	v_pk_add_f32 v[152:153], v[152:153], v[156:157]
	s_nop 1
	v_mov_b32_dpp v157, v153 row_half_mirror row_mask:0xf bank_mask:0xf
	v_mov_b32_e32 v156, v152
	s_nop 1
	v_permlane32_swap_b32_e32 v156, v152
	v_lshl_add_u32 v2, s54, 7, v147
	s_and_b32 s53, s23, 15
	s_lshl_b64 s[22:23], s[0:1], 11
	v_ashrrev_i32_e32 v3, 31, v2
	s_waitcnt lgkmcnt(0)
	v_pk_add_f32 v[152:153], v[152:153], v[156:157]
	s_or_b32 s22, s22, s26
	v_pk_fma_f32 v[180:181], v[152:153], s[38:39], v[136:137] op_sel_hi:[1,0,0]
	v_lshlrev_b64 v[2:3], s3, v[2:3]
	v_mul_f32_e32 v1, 0x4b800000, v181
	v_cmp_gt_f32_e32 vcc, s33, v181
	ds_write_b128 v229, v[92:95] offset:18432
	ds_write_b128 v231, v[64:67] offset:57344
	v_cndmask_b32_e32 v1, v181, v1, vcc
	v_rsq_f32_e32 v1, v1
	v_lshl_add_u64 v[96:97], v[114:115], 0, s[20:21]
	s_lshl_b32 s26, s53, 7
	global_load_dwordx4 v[100:103], v[96:97], off offset:16
	global_load_dwordx4 v[104:107], v[96:97], off
	global_load_dwordx4 v[92:95], v[96:97], off offset:144
	s_nop 0
	global_load_dwordx4 v[96:99], v[96:97], off offset:128
	v_mul_f32_e32 v135, 0x45800000, v1
	v_cndmask_b32_e32 v136, v1, v135, vcc
	v_pk_mul_f32 v[152:153], v[136:137], v[232:233] op_sel_hi:[0,1]
	v_pk_mul_f32 v[88:89], v[88:89], v[152:153]
	v_pk_mul_f32 v[152:153], v[136:137], v[158:159] op_sel_hi:[0,1]
	v_pk_mul_f32 v[90:91], v[90:91], v[152:153]
	v_cvt_pk_bf16_f32 v88, v88, v89
	v_cvt_pk_bf16_f32 v89, v90, v91
	v_pk_mul_f32 v[90:91], v[136:137], v[154:155] op_sel_hi:[0,1]
	v_pk_mul_f32 v[84:85], v[84:85], v[90:91]
	v_mov_b32_e32 v135, v0
	v_cvt_pk_bf16_f32 v90, v84, v85
	v_pk_mul_f32 v[84:85], v[136:137], v[150:151] op_sel_hi:[0,1]
	v_lshl_add_u64 v[136:137], s[22:23], 0, v[2:3]
	v_lshlrev_b64 v[162:163], 11, v[136:137]
	v_pk_mul_f32 v[84:85], v[86:87], v[84:85]
	v_lshl_add_u64 v[2:3], s[28:29], 0, v[162:163]
	v_cvt_pk_bf16_f32 v91, v84, v85
	v_lshl_add_u64 v[2:3], v[2:3], 0, s[26:27]
	ds_write_b128 v229, v[88:91] offset:27648
	ds_write_b128 v230, v[72:75] offset:57344
	v_lshl_add_u64 v[2:3], v[2:3], 0, v[134:135]
	global_load_dwordx4 v[88:91], v[2:3], off
	global_load_dwordx4 v[84:87], v[2:3], off offset:64
	s_waitcnt lgkmcnt(0)
	s_barrier
; __device__ __forceinline__ void attn_phase(LAS unsigned char* lds, const bf16* PROJ, const bf16* Ygate, bf16* OG0, bf16* OG1, bf16* OG2, float* LSE, const float* qnw, const float* knw, int bx, int G) {
;     ...
;         if (t + 2 * G < 3072) AT_LOAD(t + 2 * G, half);
	s_mul_i32 s20, s84, 3
	s_add_i32 s20, s20, s51
	v_cmp_gt_f32_e64 s[0:1], s33, v180
	s_cmpk_gt_i32 s20, 0xbff
	s_cbranch_scc1 .LBB0_319
	s_ashr_i32 s22, s20, 4
	s_mul_hi_i32 s23, s22, 0x55555556
	s_lshr_b32 s26, s23, 31
	s_add_i32 s23, s23, s26
	s_and_b32 s21, s20, 15
	s_mul_i32 s23, s23, 3
	s_mul_hi_i32 s20, s20, 0x2aaaaaab
	s_sub_i32 s23, s22, s23
	s_lshr_b32 s22, s20, 31
	s_ashr_i32 s20, s20, 3
	s_add_i32 s20, s20, s22
	s_ashr_i32 s22, s20, 4
	s_lshl_b32 s26, s23, 1
	s_lshl_b32 s20, s20, 6
	s_lshl_b32 s30, -1, s26
	s_mulk_i32 s23, 0xc00
	s_and_b32 s20, s20, 0x3c0
	s_andn2_b32 s30, s21, s30
	s_lshr_b32 s21, s21, s26
	s_or_b32 s20, s23, s20
	s_ashr_i32 s23, s22, 31
	s_lshl_b32 s51, s21, 7
	s_lshl_b64 s[22:23], s[22:23], 11
	s_ashr_i32 s21, s20, 31
	s_or_b32 s22, s22, s30
	s_lshl_b64 s[30:31], s[20:21], 1
	v_mov_b32_e32 v30, v0
	v_mov_b32_e32 v31, v0
	v_add_u32_e32 v76, s51, v182
	s_add_u32 s38, s34, s30
	v_mov_b32_e32 v28, v0
	v_mov_b32_e32 v29, v0
	v_mov_b64_e32 v[34:35], v[30:31]
	v_mov_b64_e32 v[38:39], v[30:31]
	s_addc_u32 s39, s35, s31
	v_cmp_lt_i32_e32 vcc, -1, v76
	v_lshlrev_b32_e32 v78, 1, v108
	v_mov_b64_e32 v[32:33], v[28:29]
	v_mov_b64_e32 v[36:37], v[28:29]
	s_and_saveexec_b64 s[30:31], vcc
	s_cbranch_execz .LBB0_312
	v_mov_b32_e32 v77, v0
	v_lshlrev_b64 v[2:3], s26, v[76:77]
	v_lshl_add_u64 v[2:3], v[2:3], 0, s[22:23]
	v_mov_b64_e32 v[32:33], s[38:39]
	s_movk_i32 s55, 0x4800
	v_mad_u64_u32 v[32:33], vcc, v2, s55, v[32:33]
	v_mov_b32_e32 v2, v33
	v_mad_u64_u32 v[2:3], vcc, v3, s55, v[2:3]
	v_mov_b32_e32 v33, v2
	v_mov_b32_e32 v79, v0
	v_lshl_add_u64 v[2:3], v[32:33], 0, v[78:79]
	v_add_co_u32_e32 v36, vcc, 0x1000, v2
	s_nop 1
	v_addc_co_u32_e32 v37, vcc, 0, v3, vcc
	global_load_dwordx4 v[32:35], v[2:3], off offset:2048
	s_nop 0
	global_load_dwordx4 v[36:39], v[36:37], off

; #define LAS __attribute__((address_space(3)))
; __device__ __forceinline__ unsigned pk2(float lo, float hi) { f32x2_t v = {lo, hi}; bf16x2_t b = __builtin_convertvector(v, bf16x2_t); return __builtin_bit_cast(unsigned, b); }
; __device__ __forceinline__ f32x4 mfma16(bf16x8 a, bf16x8 b, f32x4 c) { return __builtin_amdgcn_mfma_f32_16x16x32_bf16(a, b, c, 0, 0, 0); }
; __device__ __forceinline__ void attn_phase(LAS unsigned char* lds, const bf16* PROJ, const bf16* Ygate, bf16* OG0, bf16* OG1, bf16* OG2, float* LSE, const float* qnw, const float* knw, int bx, int G) {
;     ...
;         mx = fmaxf(mx, __shfl_xor(mx, 16)); mx = fmaxf(mx, __shfl_xor(mx, 32));
;         float sum = 0.f;
; #pragma unroll
;         for (int t9 = 0; t9 < 9; ++t9)
; #pragma unroll
;             for (int rr = 0; rr < 4; ++rr) { const float p = __expf(sc[t9][rr] - mx); sc[t9][rr] = p; sum += p; }
;         sum += __shfl_xor(sum, 16); sum += __shfl_xor(sum, 32);
;         const float lse = mx + __logf(sum), inv = 1.f / sum;
;         f32x4 oacc[4];
; #pragma unroll
;         for (int dt = 0; dt < 4; ++dt) oacc[dt] = (f32x4){0.f, 0.f, 0.f, 0.f};
; #pragma unroll
;         for (int k2 = 0; k2 < 5; ++k2) {
;             const int T0 = w + 2 * k2;
;             if (T0 + 1 >= tlo) {
;                 v4u bpu; bpu.x = pk2(sc[2 * k2][0], sc[2 * k2][1]); bpu.y = pk2(sc[2 * k2][2], sc[2 * k2][3]);
;                 if (k2 < 4) { bpu.z = pk2(sc[(2 * k2 + 1) % 9][0], sc[(2 * k2 + 1) % 9][1]); bpu.w = pk2(sc[(2 * k2 + 1) % 9][2], sc[(2 * k2 + 1) % 9][3]); } else { bpu.z = 0u; bpu.w = 0u; }
;                 const bf16x8 bp = __builtin_bit_cast(bf16x8, bpu);
;                 const LAS bf16* vb = Vs + (16 * T0 + 4 * g4 + (l16 >> 2)) * 80 + 8 * (l16 & 3);
; #pragma unroll
;                 for (int dt = 0; dt < 4; ++dt) {
;                     const int co = 32 * (dt >> 1) + 4 * (dt & 1);
;                     const v4i16_t lo = __builtin_amdgcn_ds_read_tr16_b64_v4i16((LAS v4i16_t*)(vb + co));
;                     v4i16_t hi = (v4i16_t){0, 0, 0, 0};
;                     if (k2 < 4) hi = __builtin_amdgcn_ds_read_tr16_b64_v4i16((LAS v4i16_t*)(vb + 16 * 80 + co));
;                     oacc[dt] = mfma16((bf16x8){lo[0], lo[1], lo[2], lo[3], hi[0], hi[1], hi[2], hi[3]}, bp, oacc[dt]);
.LBB0_340:
	v_mov_b32_e32 v98, v135
	s_nop 1
	v_permlane16_swap_b32_e32 v98, v135
	v_max_f32_e32 v99, v135, v135
	s_add_i32 s0, s0, -1
	s_cmp_lt_i32 s50, s0
	s_waitcnt lgkmcnt(0)
	v_max_f32_e32 v98, v98, v98
	v_max_f32_e32 v98, v99, v98
	v_mov_b32_e32 v99, v98
	s_nop 1
	v_permlane32_swap_b32_e32 v99, v98
	s_waitcnt lgkmcnt(0)
	v_max_f32_e32 v99, v99, v99
	v_max_f32_e32 v164, v98, v99
	v_sub_f32_e32 v98, v101, v164
	v_sub_f32_e32 v101, v165, v164
	v_mul_f32_e32 v101, 0x3fb8aa3b, v101
	v_exp_f32_e32 v244, v101
	v_sub_f32_e32 v101, v166, v164
	v_mul_f32_e32 v101, 0x3fb8aa3b, v101
	v_exp_f32_e32 v245, v101
	v_sub_f32_e32 v101, v167, v164
	v_mul_f32_e32 v101, 0x3fb8aa3b, v101
	v_exp_f32_e32 v246, v101
	v_sub_f32_e32 v101, v103, v164
	v_mul_f32_e32 v101, 0x3fb8aa3b, v101
	v_exp_f32_e32 v247, v101
	v_sub_f32_e32 v101, v102, v164
	v_mul_f32_e32 v101, 0x3fb8aa3b, v101
	v_exp_f32_e32 v248, v101
	v_sub_f32_e32 v101, v169, v164
	v_mul_f32_e32 v101, 0x3fb8aa3b, v101
	v_sub_f32_e32 v92, v92, v164
	v_exp_f32_e32 v249, v101
	v_sub_f32_e32 v101, v170, v164
	v_sub_f32_e32 v93, v93, v164
	v_mul_f32_e32 v92, 0x3fb8aa3b, v92
	v_mul_f32_e32 v101, 0x3fb8aa3b, v101
	v_sub_f32_e32 v94, v94, v164
	v_mul_f32_e32 v93, 0x3fb8aa3b, v93
	v_exp_f32_e32 v92, v92
	v_exp_f32_e32 v154, v101
	v_sub_f32_e32 v101, v168, v164
	v_sub_f32_e32 v3, v3, v164
	v_mul_f32_e32 v94, 0x3fb8aa3b, v94
	v_exp_f32_e32 v93, v93
	v_mul_f32_e32 v101, 0x3fb8aa3b, v101
	v_mul_f32_e32 v3, 0x3fb8aa3b, v3
	v_exp_f32_e32 v94, v94
	v_exp_f32_e32 v155, v101
	v_sub_f32_e32 v101, v175, v164
	v_exp_f32_e32 v99, v3
	v_mul_f32_e32 v101, 0x3fb8aa3b, v101
	v_add_f32_e32 v3, 0, v92
	v_exp_f32_e32 v180, v101
	v_sub_f32_e32 v101, v173, v164
	v_add_f32_e32 v3, v93, v3
	v_mul_f32_e32 v101, 0x3fb8aa3b, v101
	v_sub_f32_e32 v1, v1, v164
	v_add_f32_e32 v3, v94, v3
	v_exp_f32_e32 v181, v101
	v_sub_f32_e32 v101, v174, v164
	v_add_f32_e32 v104, v99, v3
	v_mul_f32_e32 v1, 0x3fb8aa3b, v1
	v_sub_f32_e32 v3, v100, v164
	v_mul_f32_e32 v101, 0x3fb8aa3b, v101
	v_exp_f32_e32 v1, v1
	v_mul_f32_e32 v3, 0x3fb8aa3b, v3
	v_exp_f32_e32 v231, v101
	v_sub_f32_e32 v101, v172, v164
	v_exp_f32_e32 v3, v3
	v_mul_f32_e32 v98, 0x3fb8aa3b, v98
	v_sub_f32_e32 v95, v95, v164
	v_mul_f32_e32 v101, 0x3fb8aa3b, v101
	v_exp_f32_e32 v98, v98
	v_mul_f32_e32 v95, 0x3fb8aa3b, v95
	v_exp_f32_e32 v232, v101
	v_sub_f32_e32 v101, v171, v164
	v_exp_f32_e32 v95, v95
	v_mul_f32_e32 v101, 0x3fb8aa3b, v101
	v_add_f32_e32 v100, v1, v104
	v_exp_f32_e32 v234, v101
	v_sub_f32_e32 v101, v177, v164
	v_add_f32_e32 v100, v3, v100
	v_mul_f32_e32 v101, 0x3fb8aa3b, v101
	v_add_f32_e32 v100, v98, v100
	v_exp_f32_e32 v238, v101
	v_sub_f32_e32 v101, v178, v164
	v_add_f32_e32 v100, v95, v100
	v_mul_f32_e32 v101, 0x3fb8aa3b, v101
	v_add_f32_e32 v100, v244, v100
	v_exp_f32_e32 v178, v101
	v_sub_f32_e32 v101, v176, v164
	v_add_f32_e32 v100, v245, v100
	v_mul_f32_e32 v101, 0x3fb8aa3b, v101
	v_add_f32_e32 v100, v246, v100
	v_exp_f32_e32 v239, v101
	v_sub_f32_e32 v101, v237, v164
	v_add_f32_e32 v100, v247, v100
	v_mul_f32_e32 v101, 0x3fb8aa3b, v101
	v_add_f32_e32 v100, v248, v100
	v_exp_f32_e32 v170, v101
	v_sub_f32_e32 v101, v235, v164
	v_add_f32_e32 v100, v249, v100
	v_mul_f32_e32 v101, 0x3fb8aa3b, v101
	v_add_f32_e32 v100, v154, v100
	v_exp_f32_e32 v171, v101
	v_sub_f32_e32 v101, v236, v164
	v_add_f32_e32 v100, v155, v100
	v_mul_f32_e32 v101, 0x3fb8aa3b, v101
	v_add_f32_e32 v100, v180, v100
	v_exp_f32_e32 v172, v101
	v_sub_f32_e32 v101, v233, v164
	v_add_f32_e32 v100, v181, v100
	v_mul_f32_e32 v101, 0x3fb8aa3b, v101
	v_add_f32_e32 v100, v231, v100
	v_exp_f32_e32 v173, v101
	v_sub_f32_e32 v101, v179, v164
	v_add_f32_e32 v100, v232, v100
	v_mul_f32_e32 v101, 0x3fb8aa3b, v101
	v_add_f32_e32 v100, v234, v100
	v_exp_f32_e32 v174, v101
	v_sub_f32_e32 v101, v241, v164
	v_add_f32_e32 v100, v238, v100
	v_mul_f32_e32 v101, 0x3fb8aa3b, v101
	v_add_f32_e32 v100, v178, v100
	v_exp_f32_e32 v175, v101
	v_sub_f32_e32 v101, v242, v164
	v_add_f32_e32 v100, v239, v100
	v_mul_f32_e32 v101, 0x3fb8aa3b, v101
	v_add_f32_e32 v100, v170, v100
	v_exp_f32_e32 v176, v101
	v_sub_f32_e32 v101, v240, v164
	v_add_f32_e32 v100, v171, v100
	v_mul_f32_e32 v101, 0x3fb8aa3b, v101
	v_add_f32_e32 v100, v172, v100
	v_exp_f32_e32 v177, v101
	v_sub_f32_e32 v101, v243, v164
	v_sub_f32_e32 v96, v96, v164
	v_add_f32_e32 v100, v173, v100
	v_mul_f32_e32 v101, 0x3fb8aa3b, v101
	v_mul_f32_e32 v96, 0x3fb8aa3b, v96
	v_add_f32_e32 v100, v174, v100
	v_exp_f32_e32 v166, v101
	v_exp_f32_e32 v167, v96
	v_sub_f32_e32 v96, v97, v164
	v_add_f32_e32 v100, v175, v100
	v_mul_f32_e32 v96, 0x3fb8aa3b, v96
	v_sub_f32_e32 v2, v2, v164
	v_add_f32_e32 v100, v176, v100
	v_exp_f32_e32 v168, v96
	v_mul_f32_e32 v2, 0x3fb8aa3b, v2
	v_add_f32_e32 v100, v177, v100
	v_exp_f32_e32 v169, v2
	v_add_f32_e32 v2, v166, v100
	v_add_f32_e32 v2, v167, v2
	v_add_f32_e32 v2, v168, v2
	v_add_f32_e32 v2, v169, v2
	v_mov_b32_e32 v96, v2
	s_nop 1
	v_permlane16_swap_b32_e32 v96, v2
	s_waitcnt lgkmcnt(0)
	v_add_f32_e32 v135, v2, v96
	v_mov_b32_e32 v165, v135
	s_nop 1
	v_permlane32_swap_b32_e32 v165, v135
	s_cbranch_scc1 .LBB0_342
	v_add_u32_e32 v2, v184, v224
	v_cvt_pk_bf16_f32 v92, v92, v93
	v_cvt_pk_bf16_f32 v93, v94, v99
	ds_read_b64_tr_b16 v[102:103], v2 offset:39424
	ds_read_b64_tr_b16 v[100:101], v2 offset:36864
	v_cvt_pk_bf16_f32 v95, v98, v95
	ds_read_b64_tr_b16 v[98:99], v2 offset:39432
	ds_read_b64_tr_b16 v[96:97], v2 offset:36872
	ds_read_b64_tr_b16 v[150:151], v2 offset:36928
	ds_read_b64_tr_b16 v[156:157], v2 offset:36936
	ds_read_b64_tr_b16 v[152:153], v2 offset:39488
	ds_read_b64_tr_b16 v[158:159], v2 offset:39496
	v_cvt_pk_bf16_f32 v94, v1, v3
	s_waitcnt lgkmcnt(6)
	s_nop 0
	v_mfma_f32_16x16x32_bf16 v[104:107], v[100:103], v[92:95], 0
	s_waitcnt lgkmcnt(4)
	v_mfma_f32_16x16x32_bf16 v[100:103], v[96:99], v[92:95], 0
	s_waitcnt lgkmcnt(1)
	v_mfma_f32_16x16x32_bf16 v[96:99], v[150:153], v[92:95], 0
	s_waitcnt lgkmcnt(0)
	v_mfma_f32_16x16x32_bf16 v[92:95], v[156:159], v[92:95], 0
	s_cmp_lt_i32 s44, s0
	s_cbranch_scc0 .LBB0_343
	s_branch .LBB0_344
